# nt policy on MERGE gate loads only (Mg loads stay cached) plus XN1 rows
# speedup vs baseline: 1.0036x; 1.0036x over previous
;     __device__ __forceinline__ void operator()(const f32x4 (&acc)[2][2][4][2], const pg8::Unit& u, int wr, int wc, int fr, int fq) const {
;         const int br = u.pn >> 3, pn = u.pn & 7, pm = u.pm - br * 65;
;         const int row0 = pm * 256 + wr * 64 + fr, col0 = pn * 256 + wc * 32 + 8 * fq;
; #pragma unroll
;         for (int ai = 0; ai < 2; ++ai) { u32x4 gw[4][2], ow[4][2];
; #pragma unroll
;             for (int m = 0; m < 4; ++m)
; #pragma unroll
;                 for (int bj = 0; bj < 2; ++bj) { const int row = row0 + ai * 128 + m * 16, col = col0 + bj * 128;
;                     gw[m][bj] = *(const u32x4*)(Pg + (size_t)row * LDP + br * 2048 + col);
;                     if (br) ow[m][bj] = *(const u32x4*)(Mg + (size_t)row * DM + col); else ow[m][bj] = (u32x4){0u, 0u, 0u, 0u}; }
.LBB0_961:
	s_ashr_i32 s4, s67, 3
	s_mul_i32 s5, s4, 0xffffffbf
	s_add_i32 s5, s5, s28
	v_lshl_add_u32 v212, s5, 8, v201
	s_lshl_b32 s5, s67, 8
	s_and_b32 s5, s5, 0x700
	s_lshl_b32 s4, s4, 11
	v_or_b32_e32 v0, s5, v243
	s_ashr_i32 s5, s4, 31
	s_cmp_gt_u32 s67, 7
	s_cselect_b64 s[28:29], -1, 0
	s_lshl_b64 s[4:5], s[4:5], 1
	s_add_u32 s26, s62, s4
	s_addc_u32 s27, s63, s5
	v_mov_b64_e32 v[130:131], s[26:27]
	v_mad_i64_i32 v[130:131], s[4:5], v212, s3, v[130:131]
	v_lshlrev_b32_e32 v0, 1, v0
	v_lshl_add_u64 v[130:131], v[130:131], 0, v[0:1]
	global_load_dwordx4 v[186:189], v[130:131], off nt
	v_ashrrev_i32_e32 v213, 31, v212
	v_lshlrev_b64 v[132:133], 12, v[212:213]
	s_cmp_lt_u32 s67, 8
	v_lshl_add_u64 v[220:221], s[10:11], 0, v[132:133]
	v_mov_b32_e32 v158, 0
	v_mov_b32_e32 v190, 0
	v_mov_b32_e32 v191, 0
	v_mov_b32_e32 v192, 0
	v_mov_b32_e32 v193, 0
	s_movk_i32 s68, 0x4000
	s_movk_i32 s69, 0x3000
	s_movk_i32 s70, 0x1dff
	s_movk_i32 s71, 0x1000
	s_cbranch_scc1 .LBB0_963
	v_lshl_add_u64 v[132:133], v[220:221], 0, v[0:1]
	global_load_dwordx4 v[190:193], v[132:133], off
.LBB0_963:
	global_load_dwordx4 v[178:181], v[130:131], off offset:256 nt
	v_cndmask_b32_e64 v130, 0, 1, s[28:29]
	v_cmp_ne_u32_e64 s[4:5], 1, v130
	s_andn2_b64 vcc, exec, s[28:29]
	v_mov_b32_e32 v159, 0
	v_mov_b32_e32 v160, 0
	v_mov_b32_e32 v161, 0
	s_cbranch_vccnz .LBB0_965
	v_lshl_add_u64 v[130:131], v[220:221], 0, v[0:1]
	global_load_dwordx4 v[158:161], v[130:131], off offset:256
.LBB0_965:
	v_or_b32_e32 v132, 16, v212
	v_mov_b64_e32 v[130:131], s[26:27]
	v_mad_i64_i32 v[130:131], s[28:29], v132, s3, v[130:131]
	v_lshl_add_u64 v[130:131], v[130:131], 0, v[0:1]
	global_load_dwordx4 v[174:177], v[130:131], off nt
	v_ashrrev_i32_e32 v133, 31, v132
	v_lshlrev_b64 v[132:133], 12, v[132:133]
	v_lshl_add_u64 v[218:219], s[10:11], 0, v[132:133]
	v_mov_b32_e32 v142, 0
	s_and_b64 vcc, exec, s[4:5]
	v_mov_b32_e32 v182, 0
	v_mov_b32_e32 v183, 0
	v_mov_b32_e32 v184, 0
	v_mov_b32_e32 v185, 0
	v_readlane_b32 s72, v254, 19
	s_movk_i32 s74, 0x2000
	v_readlane_b32 s73, v254, 20
	s_cbranch_vccnz .LBB0_967
	v_lshl_add_u64 v[132:133], v[218:219], 0, v[0:1]
	global_load_dwordx4 v[182:185], v[132:133], off
.LBB0_967:
	global_load_dwordx4 v[166:169], v[130:131], off offset:256 nt
	s_and_b64 vcc, exec, s[4:5]
	v_mov_b32_e32 v143, 0
	v_mov_b32_e32 v144, 0
	v_mov_b32_e32 v145, 0
	s_cbranch_vccnz .LBB0_969
	v_lshl_add_u64 v[130:131], v[218:219], 0, v[0:1]
	global_load_dwordx4 v[142:145], v[130:131], off offset:256
.LBB0_969:
	v_or_b32_e32 v132, 32, v212
	v_mov_b64_e32 v[130:131], s[26:27]
	v_mad_i64_i32 v[130:131], s[28:29], v132, s3, v[130:131]
	v_lshl_add_u64 v[130:131], v[130:131], 0, v[0:1]
	global_load_dwordx4 v[162:165], v[130:131], off nt
	v_ashrrev_i32_e32 v133, 31, v132
	v_lshlrev_b64 v[132:133], 12, v[132:133]
	v_lshl_add_u64 v[216:217], s[10:11], 0, v[132:133]
	v_mov_b32_e32 v138, 0
	s_and_b64 vcc, exec, s[4:5]
	v_mov_b32_e32 v170, 0
	v_mov_b32_e32 v171, 0
	v_mov_b32_e32 v172, 0
	v_mov_b32_e32 v173, 0
	s_cbranch_vccnz .LBB0_971
	v_lshl_add_u64 v[132:133], v[216:217], 0, v[0:1]
	global_load_dwordx4 v[170:173], v[132:133], off
.LBB0_971:
	global_load_dwordx4 v[150:153], v[130:131], off offset:256 nt
	s_and_b64 vcc, exec, s[4:5]
	v_mov_b32_e32 v139, 0
	v_mov_b32_e32 v140, 0
	v_mov_b32_e32 v141, 0
	s_cbranch_vccnz .LBB0_973
	v_lshl_add_u64 v[130:131], v[216:217], 0, v[0:1]
	global_load_dwordx4 v[138:141], v[130:131], off offset:256
.LBB0_973:
	v_or_b32_e32 v130, 48, v212
	v_mov_b64_e32 v[132:133], s[26:27]
	v_mad_i64_i32 v[132:133], s[28:29], v130, s3, v[132:133]
	v_lshl_add_u64 v[132:133], v[132:133], 0, v[0:1]
	global_load_dwordx4 v[146:149], v[132:133], off nt
	v_ashrrev_i32_e32 v131, 31, v130
	v_lshlrev_b64 v[130:131], 12, v[130:131]
	v_lshl_add_u64 v[214:215], s[10:11], 0, v[130:131]
	v_mov_b32_e32 v130, 0
	s_and_b64 vcc, exec, s[4:5]
	v_mov_b32_e32 v154, 0
	v_mov_b32_e32 v155, 0
	v_mov_b32_e32 v156, 0
	v_mov_b32_e32 v157, 0
	s_cbranch_vccnz .LBB0_975
	v_lshl_add_u64 v[134:135], v[214:215], 0, v[0:1]
	global_load_dwordx4 v[154:157], v[134:135], off
.LBB0_975:
	s_nop 0
	global_load_dwordx4 v[134:137], v[132:133], off offset:256 nt
	s_and_b64 vcc, exec, s[4:5]
	v_mov_b32_e32 v131, 0
	v_mov_b32_e32 v132, 0
	v_mov_b32_e32 v133, 0
	s_cbranch_vccnz .LBB0_977
	v_lshl_add_u64 v[130:131], v[214:215], 0, v[0:1]
	global_load_dwordx4 v[130:133], v[130:131], off offset:256
; __device__ __forceinline__ unsigned pk2(float lo, float hi) { unsigned r; asm volatile("v_cvt_pk_bf16_f32 %0, %1, %2" : "=v"(r) : "v"(lo), "v"(hi)); return r; }
;     __device__ __forceinline__ void operator()(const f32x4 (&acc)[2][2][4][2], const pg8::Unit& u, int wr, int wc, int fr, int fq) const {
;     ...
;             for (int m = 0; m < 4; ++m)
; #pragma unroll
;                 for (int bj = 0; bj < 2; ++bj) { const int row = row0 + ai * 128 + m * 16, col = col0 + bj * 128;
;                     const f32x4 v0 = acc[ai][bj][m][0], v1 = acc[ai][bj][m][1]; float r[8];
; #pragma unroll
;                     for (int e = 0; e < 4; ++e) { const float a0 = e < 2 ? v0[2 * e] : v1[2 * e - 4], a1 = e < 2 ? v0[2 * e + 1] : v1[2 * e - 3];
;                         r[2 * e] = __uint_as_float(ow[m][bj][e] << 16) + __uint_as_float(gw[m][bj][e] << 16) * a0;
;                         r[2 * e + 1] = __uint_as_float(ow[m][bj][e] & 0xffff0000u) + __uint_as_float(gw[m][bj][e] & 0xffff0000u) * a1; }
;                     u32x4 w; w.x = pk2(r[0], r[1]); w.y = pk2(r[2], r[3]); w.z = pk2(r[4], r[5]); w.w = pk2(r[6], r[7]);
;                     *(u32x4*)(Mg + (size_t)row * DM + col) = w; } }
.LBB0_977:
	s_waitcnt vmcnt(0)
	v_lshlrev_b32_e32 v213, 16, v190
	v_lshlrev_b32_e32 v230, 16, v186
	v_fmac_f32_e32 v213, v126, v230
	v_and_b32_e32 v126, 0xffff0000, v190
	v_and_b32_e32 v186, 0xffff0000, v186
	v_fmac_f32_e32 v126, v127, v186
	v_lshlrev_b32_e32 v127, 16, v191
	v_lshlrev_b32_e32 v186, 16, v187
	v_fmac_f32_e32 v127, v128, v186
	v_and_b32_e32 v128, 0xffff0000, v191
	v_and_b32_e32 v186, 0xffff0000, v187
	v_fmac_f32_e32 v128, v129, v186
	v_lshlrev_b32_e32 v129, 16, v192
	v_lshlrev_b32_e32 v186, 16, v188
	v_fmac_f32_e32 v129, v118, v186
	v_and_b32_e32 v186, 0xffff0000, v192
	v_and_b32_e32 v118, 0xffff0000, v188
	v_fmac_f32_e32 v186, v119, v118
	v_lshlrev_b32_e32 v187, 16, v193
	v_lshlrev_b32_e32 v118, 16, v189
	v_fmac_f32_e32 v187, v120, v118
	v_and_b32_e32 v188, 0xffff0000, v193
	v_and_b32_e32 v118, 0xffff0000, v189
	v_fmac_f32_e32 v188, v121, v118
	v_cvt_pk_bf16_f32 v118, v213, v126
	v_cvt_pk_bf16_f32 v119, v127, v128
	v_lshl_add_u64 v[126:127], v[220:221], 0, v[0:1]
	v_cvt_pk_bf16_f32 v120, v129, v186
	v_cvt_pk_bf16_f32 v121, v187, v188
	global_store_dwordx4 v[126:127], v[118:121], off
	s_and_b64 vcc, exec, s[4:5]
	v_mov_b32_e32 v128, 0
	v_lshlrev_b32_e32 v118, 16, v158
	v_lshlrev_b32_e32 v119, 16, v178
	v_fmac_f32_e32 v118, v122, v119
	v_and_b32_e32 v119, 0xffff0000, v158
	v_and_b32_e32 v120, 0xffff0000, v178
	v_fmac_f32_e32 v119, v123, v120
	v_lshlrev_b32_e32 v120, 16, v159
	v_lshlrev_b32_e32 v121, 16, v179
	v_fmac_f32_e32 v120, v124, v121
	v_and_b32_e32 v121, 0xffff0000, v159
	v_and_b32_e32 v122, 0xffff0000, v179
	v_fmac_f32_e32 v121, v125, v122
	v_lshlrev_b32_e32 v122, 16, v160
	v_lshlrev_b32_e32 v123, 16, v180
	v_fmac_f32_e32 v122, v114, v123
	v_and_b32_e32 v123, 0xffff0000, v160
	v_and_b32_e32 v114, 0xffff0000, v180
	v_fmac_f32_e32 v123, v115, v114
	v_lshlrev_b32_e32 v124, 16, v161
	v_lshlrev_b32_e32 v114, 16, v181
	v_fmac_f32_e32 v124, v116, v114
	v_and_b32_e32 v125, 0xffff0000, v161
	v_and_b32_e32 v114, 0xffff0000, v181
	v_fmac_f32_e32 v125, v117, v114
	v_cvt_pk_bf16_f32 v114, v118, v119
	v_cvt_pk_bf16_f32 v115, v120, v121
	v_cvt_pk_bf16_f32 v116, v122, v123
	v_cvt_pk_bf16_f32 v117, v124, v125
	global_store_dwordx4 v[126:127], v[114:117], off offset:256
	v_mov_b32_e32 v126, 0
	v_mov_b32_e32 v127, 0
	v_lshlrev_b32_e32 v114, 16, v182
	v_lshlrev_b32_e32 v115, 16, v174
	v_fmac_f32_e32 v114, v110, v115
	v_and_b32_e32 v110, 0xffff0000, v182
	v_and_b32_e32 v115, 0xffff0000, v174
	v_fmac_f32_e32 v110, v111, v115
	v_lshlrev_b32_e32 v111, 16, v183
	v_lshlrev_b32_e32 v115, 16, v175
	v_fmac_f32_e32 v111, v112, v115
	v_and_b32_e32 v112, 0xffff0000, v183
	v_and_b32_e32 v115, 0xffff0000, v175
	v_fmac_f32_e32 v112, v113, v115
	v_lshlrev_b32_e32 v113, 16, v184
	v_lshlrev_b32_e32 v115, 16, v176
	v_fmac_f32_e32 v113, v102, v115
	v_and_b32_e32 v115, 0xffff0000, v184
	v_and_b32_e32 v102, 0xffff0000, v176
	v_fmac_f32_e32 v115, v103, v102
	v_lshlrev_b32_e32 v116, 16, v185
	v_lshlrev_b32_e32 v102, 16, v177
	v_fmac_f32_e32 v116, v104, v102
	v_and_b32_e32 v117, 0xffff0000, v185
	v_and_b32_e32 v102, 0xffff0000, v177
	v_fmac_f32_e32 v117, v105, v102
	v_cvt_pk_bf16_f32 v102, v114, v110
	v_cvt_pk_bf16_f32 v103, v111, v112
	v_lshl_add_u64 v[110:111], v[218:219], 0, v[0:1]
	v_cvt_pk_bf16_f32 v104, v113, v115
	v_cvt_pk_bf16_f32 v105, v116, v117
	global_store_dwordx4 v[110:111], v[102:105], off
	v_mov_b32_e32 v129, 0
	s_nop 0
	v_lshlrev_b32_e32 v102, 16, v142
	v_lshlrev_b32_e32 v103, 16, v166
	v_fmac_f32_e32 v102, v106, v103
	v_and_b32_e32 v103, 0xffff0000, v142
	v_and_b32_e32 v104, 0xffff0000, v166
	v_fmac_f32_e32 v103, v107, v104
	v_lshlrev_b32_e32 v104, 16, v143
	v_lshlrev_b32_e32 v105, 16, v167
	v_fmac_f32_e32 v104, v108, v105
	v_and_b32_e32 v105, 0xffff0000, v143
	v_and_b32_e32 v106, 0xffff0000, v167
	v_fmac_f32_e32 v105, v109, v106
	v_lshlrev_b32_e32 v106, 16, v144
	v_lshlrev_b32_e32 v107, 16, v168
	v_fmac_f32_e32 v106, v98, v107
	v_and_b32_e32 v107, 0xffff0000, v144
	v_and_b32_e32 v98, 0xffff0000, v168
	v_fmac_f32_e32 v107, v99, v98
	v_lshlrev_b32_e32 v108, 16, v145
	v_lshlrev_b32_e32 v98, 16, v169
	v_fmac_f32_e32 v108, v100, v98
	v_and_b32_e32 v109, 0xffff0000, v145
	v_and_b32_e32 v98, 0xffff0000, v169
	v_fmac_f32_e32 v109, v101, v98
	v_cvt_pk_bf16_f32 v98, v102, v103
	v_cvt_pk_bf16_f32 v99, v104, v105
	v_cvt_pk_bf16_f32 v100, v106, v107
	v_cvt_pk_bf16_f32 v101, v108, v109
	global_store_dwordx4 v[110:111], v[98:101], off offset:256
	s_nop 1
	v_lshlrev_b32_e32 v98, 16, v170
	v_lshlrev_b32_e32 v99, 16, v162
	v_fmac_f32_e32 v98, v94, v99
	v_and_b32_e32 v94, 0xffff0000, v170
	v_and_b32_e32 v99, 0xffff0000, v162
	v_fmac_f32_e32 v94, v95, v99
	v_lshlrev_b32_e32 v95, 16, v171
	v_lshlrev_b32_e32 v99, 16, v163
	v_fmac_f32_e32 v95, v96, v99
	v_and_b32_e32 v96, 0xffff0000, v171
	v_and_b32_e32 v99, 0xffff0000, v163
	v_fmac_f32_e32 v96, v97, v99
	v_lshlrev_b32_e32 v97, 16, v172
	v_lshlrev_b32_e32 v99, 16, v164
	v_fmac_f32_e32 v97, v86, v99
	v_and_b32_e32 v99, 0xffff0000, v172
	v_and_b32_e32 v86, 0xffff0000, v164
	v_fmac_f32_e32 v99, v87, v86
	v_lshlrev_b32_e32 v100, 16, v173
	v_lshlrev_b32_e32 v86, 16, v165
	v_fmac_f32_e32 v100, v88, v86
	v_and_b32_e32 v101, 0xffff0000, v173
	v_and_b32_e32 v86, 0xffff0000, v165
	v_fmac_f32_e32 v101, v89, v86
	v_cvt_pk_bf16_f32 v86, v98, v94
	v_cvt_pk_bf16_f32 v87, v95, v96
	v_lshl_add_u64 v[94:95], v[216:217], 0, v[0:1]
	v_cvt_pk_bf16_f32 v88, v97, v99
	v_cvt_pk_bf16_f32 v89, v100, v101
	global_store_dwordx4 v[94:95], v[86:89], off
	v_mov_b32_e32 v98, 0
	s_nop 0
	v_lshlrev_b32_e32 v86, 16, v138
	v_lshlrev_b32_e32 v87, 16, v150
	v_fmac_f32_e32 v86, v90, v87
	v_and_b32_e32 v87, 0xffff0000, v138
	v_and_b32_e32 v88, 0xffff0000, v150
; __device__ __forceinline__ unsigned pk2(float lo, float hi) { unsigned r; asm volatile("v_cvt_pk_bf16_f32 %0, %1, %2" : "=v"(r) : "v"(lo), "v"(hi)); return r; }
;     __device__ __forceinline__ void operator()(const f32x4 (&acc)[2][2][4][2], const pg8::Unit& u, int wr, int wc, int fr, int fq) const {
;     ...
;         for (int ai = 0; ai < 2; ++ai) { u32x4 gw[4][2], ow[4][2];
; #pragma unroll
;             for (int m = 0; m < 4; ++m)
; #pragma unroll
;                 for (int bj = 0; bj < 2; ++bj) { const int row = row0 + ai * 128 + m * 16, col = col0 + bj * 128;
;                     gw[m][bj] = *(const u32x4*)(Pg + (size_t)row * LDP + br * 2048 + col);
;                     if (br) ow[m][bj] = *(const u32x4*)(Mg + (size_t)row * DM + col); else ow[m][bj] = (u32x4){0u, 0u, 0u, 0u}; }
; #pragma unroll
;             for (int m = 0; m < 4; ++m)
; #pragma unroll
;                 for (int bj = 0; bj < 2; ++bj) { const int row = row0 + ai * 128 + m * 16, col = col0 + bj * 128;
;                     const f32x4 v0 = acc[ai][bj][m][0], v1 = acc[ai][bj][m][1]; float r[8];
; #pragma unroll
;                     for (int e = 0; e < 4; ++e) { const float a0 = e < 2 ? v0[2 * e] : v1[2 * e - 4], a1 = e < 2 ? v0[2 * e + 1] : v1[2 * e - 3];
;                         r[2 * e] = __uint_as_float(ow[m][bj][e] << 16) + __uint_as_float(gw[m][bj][e] << 16) * a0;
;                         r[2 * e + 1] = __uint_as_float(ow[m][bj][e] & 0xffff0000u) + __uint_as_float(gw[m][bj][e] & 0xffff0000u) * a1; }
;                     u32x4 w; w.x = pk2(r[0], r[1]); w.y = pk2(r[2], r[3]); w.z = pk2(r[4], r[5]); w.w = pk2(r[6], r[7]);
;                     *(u32x4*)(Mg + (size_t)row * DM + col) = w; } }
	v_fmac_f32_e32 v87, v91, v88
	v_lshlrev_b32_e32 v88, 16, v139
	v_lshlrev_b32_e32 v89, 16, v151
	v_fmac_f32_e32 v88, v92, v89
	v_and_b32_e32 v89, 0xffff0000, v139
	v_and_b32_e32 v90, 0xffff0000, v151
	v_fmac_f32_e32 v89, v93, v90
	v_lshlrev_b32_e32 v90, 16, v140
	v_lshlrev_b32_e32 v91, 16, v152
	v_fmac_f32_e32 v90, v82, v91
	v_and_b32_e32 v91, 0xffff0000, v140
	v_and_b32_e32 v82, 0xffff0000, v152
	v_fmac_f32_e32 v91, v83, v82
	v_lshlrev_b32_e32 v92, 16, v141
	v_lshlrev_b32_e32 v82, 16, v153
	v_fmac_f32_e32 v92, v84, v82
	v_and_b32_e32 v93, 0xffff0000, v141
	v_and_b32_e32 v82, 0xffff0000, v153
	v_fmac_f32_e32 v93, v85, v82
	v_cvt_pk_bf16_f32 v82, v86, v87
	v_cvt_pk_bf16_f32 v83, v88, v89
	v_cvt_pk_bf16_f32 v84, v90, v91
	v_cvt_pk_bf16_f32 v85, v92, v93
	global_store_dwordx4 v[94:95], v[82:85], off offset:256
	s_nop 1
	v_lshlrev_b32_e32 v82, 16, v154
	v_lshlrev_b32_e32 v83, 16, v146
	v_fmac_f32_e32 v82, v78, v83
	v_and_b32_e32 v78, 0xffff0000, v154
	v_and_b32_e32 v83, 0xffff0000, v146
	v_fmac_f32_e32 v78, v79, v83
	v_lshlrev_b32_e32 v79, 16, v155
	v_lshlrev_b32_e32 v83, 16, v147
	v_fmac_f32_e32 v79, v80, v83
	v_and_b32_e32 v80, 0xffff0000, v155
	v_and_b32_e32 v83, 0xffff0000, v147
	v_fmac_f32_e32 v80, v81, v83
	v_lshlrev_b32_e32 v81, 16, v156
	v_lshlrev_b32_e32 v83, 16, v148
	v_fmac_f32_e32 v81, v70, v83
	v_and_b32_e32 v83, 0xffff0000, v156
	v_and_b32_e32 v70, 0xffff0000, v148
	v_fmac_f32_e32 v83, v71, v70
	v_lshlrev_b32_e32 v84, 16, v157
	v_lshlrev_b32_e32 v70, 16, v149
	v_fmac_f32_e32 v84, v72, v70
	v_and_b32_e32 v85, 0xffff0000, v157
	v_and_b32_e32 v70, 0xffff0000, v149
	v_fmac_f32_e32 v85, v73, v70
	v_cvt_pk_bf16_f32 v70, v82, v78
	v_cvt_pk_bf16_f32 v71, v79, v80
	v_lshl_add_u64 v[78:79], v[214:215], 0, v[0:1]
	v_cvt_pk_bf16_f32 v72, v81, v83
	v_cvt_pk_bf16_f32 v73, v84, v85
	global_store_dwordx4 v[78:79], v[70:73], off
	s_nop 1
	v_lshlrev_b32_e32 v70, 16, v130
	v_lshlrev_b32_e32 v71, 16, v134
	v_fmac_f32_e32 v70, v74, v71
	v_and_b32_e32 v71, 0xffff0000, v130
	v_and_b32_e32 v72, 0xffff0000, v134
	v_fmac_f32_e32 v71, v75, v72
	v_lshlrev_b32_e32 v72, 16, v131
	v_lshlrev_b32_e32 v73, 16, v135
	v_fmac_f32_e32 v72, v76, v73
	v_and_b32_e32 v73, 0xffff0000, v131
	v_and_b32_e32 v74, 0xffff0000, v135
	v_fmac_f32_e32 v73, v77, v74
	v_lshlrev_b32_e32 v74, 16, v132
	v_lshlrev_b32_e32 v75, 16, v136
	v_fmac_f32_e32 v74, v66, v75
	v_and_b32_e32 v66, 0xffff0000, v132
	v_and_b32_e32 v75, 0xffff0000, v136
	v_fmac_f32_e32 v66, v67, v75
	v_lshlrev_b32_e32 v67, 16, v133
	v_lshlrev_b32_e32 v75, 16, v137
	v_fmac_f32_e32 v67, v68, v75
	v_and_b32_e32 v75, 0xffff0000, v133
	v_and_b32_e32 v68, 0xffff0000, v137
	v_fmac_f32_e32 v75, v69, v68
	v_cvt_pk_bf16_f32 v68, v70, v71
	v_cvt_pk_bf16_f32 v69, v72, v73
	v_cvt_pk_bf16_f32 v70, v74, v66
	v_cvt_pk_bf16_f32 v71, v67, v75
	v_add_u32_e32 v72, 0x80, v212
	v_mov_b64_e32 v[66:67], s[26:27]
	v_mad_i64_i32 v[66:67], s[28:29], v72, s3, v[66:67]
	v_lshl_add_u64 v[66:67], v[66:67], 0, v[0:1]
	global_load_dwordx4 v[122:125], v[66:67], off nt
	v_ashrrev_i32_e32 v73, 31, v72
	global_store_dwordx4 v[78:79], v[68:71], off offset:256
	s_nop 1
	v_lshlrev_b64 v[68:69], 12, v[72:73]
	v_lshl_add_u64 v[136:137], s[10:11], 0, v[68:69]
	s_cbranch_vccnz .LBB0_979
	v_lshl_add_u64 v[68:69], v[136:137], 0, v[0:1]
	global_load_dwordx4 v[126:129], v[68:69], off
.LBB0_979:
	global_load_dwordx4 v[114:117], v[66:67], off offset:256 nt
	s_and_b64 vcc, exec, s[4:5]
	v_mov_b32_e32 v99, 0
	v_mov_b32_e32 v100, 0
	v_mov_b32_e32 v101, 0
	s_cbranch_vccnz .LBB0_981
	v_lshl_add_u64 v[66:67], v[136:137], 0, v[0:1]
	global_load_dwordx4 v[98:101], v[66:67], off offset:256
.LBB0_981:
	v_add_u32_e32 v68, 0x90, v212
	v_mov_b64_e32 v[66:67], s[26:27]
	v_mad_i64_i32 v[66:67], s[28:29], v68, s3, v[66:67]
	v_lshl_add_u64 v[66:67], v[66:67], 0, v[0:1]
	global_load_dwordx4 v[110:113], v[66:67], off nt
	v_ashrrev_i32_e32 v69, 31, v68
	v_lshlrev_b64 v[68:69], 12, v[68:69]
	v_lshl_add_u64 v[134:135], s[10:11], 0, v[68:69]
	v_mov_b32_e32 v82, 0
	s_and_b64 vcc, exec, s[4:5]
	v_mov_b32_e32 v118, 0
	v_mov_b32_e32 v119, 0
	v_mov_b32_e32 v120, 0
	v_mov_b32_e32 v121, 0
	s_cbranch_vccnz .LBB0_983
	v_lshl_add_u64 v[68:69], v[134:135], 0, v[0:1]
	global_load_dwordx4 v[118:121], v[68:69], off
.LBB0_983:
	global_load_dwordx4 v[102:105], v[66:67], off offset:256 nt
	s_and_b64 vcc, exec, s[4:5]
	v_mov_b32_e32 v83, 0
	v_mov_b32_e32 v84, 0
	v_mov_b32_e32 v85, 0
	s_cbranch_vccnz .LBB0_985
	v_lshl_add_u64 v[66:67], v[134:135], 0, v[0:1]
	global_load_dwordx4 v[82:85], v[66:67], off offset:256
.LBB0_985:
	v_add_u32_e32 v68, 0xa0, v212
	v_mov_b64_e32 v[66:67], s[26:27]
	v_mad_i64_i32 v[66:67], s[28:29], v68, s3, v[66:67]
	v_lshl_add_u64 v[66:67], v[66:67], 0, v[0:1]
	global_load_dwordx4 v[94:97], v[66:67], off nt
	v_ashrrev_i32_e32 v69, 31, v68
	v_lshlrev_b64 v[68:69], 12, v[68:69]
	v_lshl_add_u64 v[132:133], s[10:11], 0, v[68:69]
	v_mov_b32_e32 v74, 0
	s_and_b64 vcc, exec, s[4:5]
	v_mov_b32_e32 v106, 0
	v_mov_b32_e32 v107, 0
	v_mov_b32_e32 v108, 0
	v_mov_b32_e32 v109, 0
	s_cbranch_vccnz .LBB0_987
	v_lshl_add_u64 v[68:69], v[132:133], 0, v[0:1]
	global_load_dwordx4 v[106:109], v[68:69], off
.LBB0_987:
	global_load_dwordx4 v[86:89], v[66:67], off offset:256 nt
	s_and_b64 vcc, exec, s[4:5]
	v_mov_b32_e32 v75, 0
	v_mov_b32_e32 v76, 0
	v_mov_b32_e32 v77, 0
	s_cbranch_vccnz .LBB0_989
	v_lshl_add_u64 v[66:67], v[132:133], 0, v[0:1]
	global_load_dwordx4 v[74:77], v[66:67], off offset:256
.LBB0_989:
	v_add_u32_e32 v66, 0xb0, v212
	v_mov_b64_e32 v[68:69], s[26:27]
	v_mad_i64_i32 v[68:69], s[26:27], v66, s3, v[68:69]
	v_lshl_add_u64 v[68:69], v[68:69], 0, v[0:1]
	global_load_dwordx4 v[78:81], v[68:69], off nt
	v_ashrrev_i32_e32 v67, 31, v66
	v_lshlrev_b64 v[66:67], 12, v[66:67]
	v_lshl_add_u64 v[130:131], s[10:11], 0, v[66:67]
	v_mov_b32_e32 v66, 0
	s_and_b64 vcc, exec, s[4:5]
	v_mov_b32_e32 v90, 0
	v_mov_b32_e32 v91, 0
	v_mov_b32_e32 v92, 0
	v_mov_b32_e32 v93, 0
	s_cbranch_vccnz .LBB0_991
	v_lshl_add_u64 v[70:71], v[130:131], 0, v[0:1]
	global_load_dwordx4 v[90:93], v[70:71], off
.LBB0_991:
	s_nop 0
	global_load_dwordx4 v[70:73], v[68:69], off offset:256 nt
	s_and_b64 vcc, exec, s[4:5]
	v_mov_b32_e32 v67, 0
	v_mov_b32_e32 v68, 0
	v_mov_b32_e32 v69, 0
	s_cbranch_vccnz .LBB0_993
	v_lshl_add_u64 v[66:67], v[130:131], 0, v[0:1]
	global_load_dwordx4 v[66:69], v[66:67], off offset:256
